# P0 weight cast/transpose: the bf16 weight rows are written with non-temporal stores
# speedup vs baseline: 1.0025x; 1.0025x over previous
.LBB0_7:
	ds_read2_b32 v[44:45], v28 offset1:33
	s_mul_hi_i32 s13, s10, 0x1800000
	s_mul_i32 s10, s10, 0x1800000
	v_readlane_b32 s18, v252, 18
	s_add_u32 s10, s18, s10
	s_waitcnt vmcnt(1) lgkmcnt(0)
	v_mul_f32_e32 v21, v6, v44
	v_mul_f32_e32 v44, v7, v45
	v_cvt_pk_bf16_f32 v44, v21, v44
	ds_read2_b32 v[46:47], v28 offset0:66 offset1:99
	v_readlane_b32 s18, v252, 19
	s_addc_u32 s13, s18, s13
	s_lshl_b64 s[16:17], s[16:17], 1
	s_add_u32 s16, s10, s16
	s_waitcnt lgkmcnt(0)
	v_mul_f32_e32 v45, v9, v47
	v_mul_f32_e32 v21, v8, v46
	v_cvt_pk_bf16_f32 v45, v21, v45
	ds_read2_b32 v[46:47], v28 offset0:132 offset1:165
	v_mov_b32_e32 v21, v11
	s_addc_u32 s17, s13, s17
	v_lshl_add_u64 v[50:51], s[16:17], 0, v[20:21]
	s_waitcnt vmcnt(0) lgkmcnt(0)
	v_mul_f32_e32 v46, v2, v46
	v_mul_f32_e32 v47, v3, v47
	v_cvt_pk_bf16_f32 v46, v46, v47
	ds_read2_b32 v[48:49], v28 offset0:198 offset1:231
	s_waitcnt lgkmcnt(0)
	v_mul_f32_e32 v47, v5, v49
	v_mul_f32_e32 v21, v4, v48
	v_cvt_pk_bf16_f32 v47, v21, v47
	ds_read2_b32 v[52:53], v28 offset0:8 offset1:41
	v_or_b32_e32 v48, s12, v1
	v_ashrrev_i32_e32 v49, 31, v48
	v_lshlrev_b64 v[48:49], 12, v[48:49]
	v_lshl_add_u64 v[48:49], v[50:51], 0, v[48:49]
	global_store_dwordx4 v[48:49], v[44:47], off nt
	s_waitcnt lgkmcnt(0)
	v_mul_f32_e32 v21, v6, v52
	v_or_b32_e32 v52, s12, v13
	v_mul_f32_e32 v44, v7, v53
	v_cvt_pk_bf16_f32 v44, v21, v44
	ds_read2_b32 v[46:47], v28 offset0:74 offset1:107
	v_ashrrev_i32_e32 v53, 31, v52
	v_lshlrev_b64 v[52:53], 12, v[52:53]
	v_lshl_add_u64 v[52:53], v[50:51], 0, v[52:53]
	s_waitcnt lgkmcnt(0)
	v_mul_f32_e32 v45, v9, v47
	v_mul_f32_e32 v21, v8, v46
	v_cvt_pk_bf16_f32 v45, v21, v45
	ds_read2_b32 v[46:47], v28 offset0:140 offset1:173
	s_waitcnt lgkmcnt(0)
	v_mul_f32_e32 v21, v2, v46
	v_mul_f32_e32 v46, v3, v47
	v_cvt_pk_bf16_f32 v46, v21, v46
	ds_read2_b32 v[48:49], v28 offset0:206 offset1:239
	s_waitcnt lgkmcnt(0)
	v_mul_f32_e32 v47, v5, v49
	v_mul_f32_e32 v21, v4, v48
	v_cvt_pk_bf16_f32 v47, v21, v47
	ds_read2_b32 v[48:49], v28 offset0:16 offset1:49
	global_store_dwordx4 v[52:53], v[44:47], off nt
	v_or_b32_e32 v52, s12, v22
	v_ashrrev_i32_e32 v53, 31, v52
	v_lshlrev_b64 v[52:53], 12, v[52:53]
	s_waitcnt lgkmcnt(0)
	v_mul_f32_e32 v44, v7, v49
	v_mul_f32_e32 v21, v6, v48
	v_cvt_pk_bf16_f32 v44, v21, v44
	ds_read2_b32 v[46:47], v28 offset0:82 offset1:115
	v_lshl_add_u64 v[52:53], v[50:51], 0, v[52:53]
	s_waitcnt lgkmcnt(0)
	v_mul_f32_e32 v45, v9, v47
	v_mul_f32_e32 v21, v8, v46
	v_cvt_pk_bf16_f32 v45, v21, v45
	ds_read2_b32 v[46:47], v28 offset0:148 offset1:181
	s_waitcnt lgkmcnt(0)
	v_mul_f32_e32 v21, v2, v46
	v_mul_f32_e32 v46, v3, v47
	v_cvt_pk_bf16_f32 v46, v21, v46
	ds_read2_b32 v[48:49], v28 offset0:214 offset1:247
	s_waitcnt lgkmcnt(0)
	v_mul_f32_e32 v47, v5, v49
	v_mul_f32_e32 v21, v4, v48
	v_cvt_pk_bf16_f32 v47, v21, v47
	ds_read2_b32 v[48:49], v28 offset0:24 offset1:57
	global_store_dwordx4 v[52:53], v[44:47], off nt
	s_waitcnt lgkmcnt(0)
	v_mul_f32_e32 v6, v6, v48
	v_mul_f32_e32 v7, v7, v49
	v_cvt_pk_bf16_f32 v6, v6, v7
	ds_read2_b32 v[44:45], v28 offset0:90 offset1:123
	s_waitcnt lgkmcnt(0)
	v_mul_f32_e32 v7, v8, v44
	v_mul_f32_e32 v8, v9, v45
	v_cvt_pk_bf16_f32 v7, v7, v8
	ds_read2_b32 v[8:9], v28 offset0:156 offset1:189
	v_or_b32_e32 v44, s12, v23
	v_ashrrev_i32_e32 v45, 31, v44
	v_lshlrev_b64 v[44:45], 12, v[44:45]
	s_waitcnt lgkmcnt(0)
	v_mul_f32_e32 v2, v2, v8
	v_mul_f32_e32 v3, v3, v9
	v_cvt_pk_bf16_f32 v8, v2, v3
	ds_read2_b32 v[2:3], v28 offset0:222 offset1:255
	s_waitcnt lgkmcnt(0)
	v_mul_f32_e32 v2, v4, v2
	v_mul_f32_e32 v3, v5, v3
	v_cvt_pk_bf16_f32 v9, v2, v3
	v_lshl_add_u64 v[2:3], v[50:51], 0, v[44:45]
	global_store_dwordx4 v[2:3], v[6:9], off nt
	s_waitcnt lgkmcnt(0)

.LBB0_11:
	s_cmpk_gt_u32 s21, 0x3fff
	s_cbranch_scc0 .LBB0_45
	s_cmpk_gt_u32 s21, 0x4fff
	s_cbranch_scc0 .LBB0_39
	s_cmpk_gt_u32 s21, 0x5fff
	s_cbranch_scc0 .LBB0_33
	s_cmpk_gt_u32 s21, 0x6fff
	s_cbranch_scc0 .LBB0_30
	s_cmpk_gt_u32 s21, 0xc7ff
	s_cbranch_scc0 .LBB0_24
	s_cmp_gt_u32 s21, 0x11fff
	s_cbranch_scc0 .LBB0_18
	s_add_i32 s10, s21, 0xe000
	s_and_b32 s12, s10, 0xffff
	s_mul_i32 s12, s12, 0xba2f
	s_lshr_b32 s12, s12, 28
	s_mul_i32 s13, s12, 0x2c00000
	s_add_u32 s13, s90, s13
	s_addc_u32 s16, s91, 0
	s_mul_i32 s17, s12, 0x1600000
	v_readlane_b32 s18, v252, 30
	s_add_u32 s17, s18, s17
	v_readlane_b32 s18, v252, 31
	s_mulk_i32 s12, 0x1600
	s_addc_u32 s18, s18, 0
	s_sub_i32 s10, s10, s12
	s_and_b32 s19, s10, 0x1fc0
	s_lshl_b32 s10, s10, 5
	s_and_b32 s10, s10, 0x7e0
	v_or_b32_e32 v21, s19, v22
	s_lshl_b32 s12, s10, 2
	v_lshlrev_b32_e32 v44, 13, v21
	v_or_b32_e32 v21, s19, v23
	s_add_u32 s12, s13, s12
	v_lshlrev_b32_e32 v46, 13, v21
	v_or_b32_e32 v21, s19, v24
	s_addc_u32 s13, s16, 0
	v_or_b32_e32 v2, s19, v1
	v_or_b32_e32 v4, s19, v13
	v_lshlrev_b32_e32 v52, 13, v21
	v_or_b32_e32 v21, s19, v25
	v_lshl_add_u64 v[64:65], s[12:13], 0, v[10:11]
	v_lshlrev_b32_e32 v2, 13, v2
	v_mov_b32_e32 v3, v11
	v_lshlrev_b32_e32 v4, 13, v4
	v_mov_b32_e32 v5, v11
	v_mov_b32_e32 v45, v11
	v_mov_b32_e32 v47, v11
	v_mov_b32_e32 v53, v11
	v_lshlrev_b32_e32 v54, 13, v21
	v_mov_b32_e32 v55, v11
	v_lshl_add_u64 v[2:3], v[64:65], 0, v[2:3]
	v_lshl_add_u64 v[6:7], v[64:65], 0, v[4:5]
	v_lshl_add_u64 v[44:45], v[64:65], 0, v[44:45]
	v_lshl_add_u64 v[48:49], v[64:65], 0, v[46:47]
	v_lshl_add_u64 v[52:53], v[64:65], 0, v[52:53]
	v_lshl_add_u64 v[56:57], v[64:65], 0, v[54:55]
	global_load_dwordx4 v[2:5], v[2:3], off nt
	s_nop 0
	global_load_dwordx4 v[6:9], v[6:7], off nt
	s_nop 0
	global_load_dwordx4 v[44:47], v[44:45], off nt
	s_nop 0
	global_load_dwordx4 v[48:51], v[48:49], off nt
	s_nop 0
	global_load_dwordx4 v[52:55], v[52:53], off nt
	s_nop 0
	global_load_dwordx4 v[56:59], v[56:57], off nt
	v_or_b32_e32 v21, s19, v26
	v_lshlrev_b32_e32 v60, 13, v21
	v_mov_b32_e32 v61, v11
	v_lshl_add_u64 v[60:61], v[64:65], 0, v[60:61]
	v_or_b32_e32 v21, s19, v27
	global_load_dwordx4 v[60:63], v[60:61], off nt
	v_lshlrev_b32_e32 v66, 13, v21
	v_mov_b32_e32 v67, v11
	v_lshl_add_u64 v[64:65], v[64:65], 0, v[66:67]
	global_load_dwordx4 v[64:67], v[64:65], off nt
	s_lshl_b32 s12, s19, 1
	s_add_u32 s12, s17, s12
	v_mov_b32_e32 v21, v11
	s_addc_u32 s13, s18, 0
	s_waitcnt vmcnt(7)
	ds_write2_b32 v29, v2, v3 offset1:1
	ds_write2_b32 v29, v4, v5 offset0:2 offset1:3
	s_waitcnt vmcnt(6)
	ds_write2_b32 v30, v6, v7 offset1:1
	ds_write2_b32 v31, v8, v9 offset1:1
	s_waitcnt vmcnt(5)
	ds_write2_b32 v32, v44, v45 offset1:1
	ds_write2_b32 v33, v46, v47 offset1:1
	s_waitcnt vmcnt(4)
	ds_write2_b32 v34, v48, v49 offset1:1
	ds_write2_b32 v35, v50, v51 offset1:1
	s_waitcnt vmcnt(3)
	ds_write2_b32 v36, v52, v53 offset1:1
	ds_write2_b32 v37, v54, v55 offset1:1
	s_waitcnt vmcnt(2)
	ds_write2_b32 v38, v56, v57 offset1:1
	ds_write2_b32 v39, v58, v59 offset1:1
	s_waitcnt vmcnt(1)
	ds_write2_b32 v40, v60, v61 offset1:1
	ds_write2_b32 v41, v62, v63 offset1:1
	s_waitcnt vmcnt(0)
	ds_write2_b32 v42, v64, v65 offset1:1
	ds_write2_b32 v43, v66, v67 offset1:1
	s_waitcnt lgkmcnt(0)
	ds_read2_b32 v[2:3], v28 offset1:33
	s_waitcnt lgkmcnt(0)
	v_cvt_pk_bf16_f32 v2, v2, v3
	ds_read2_b32 v[4:5], v28 offset0:66 offset1:99
	s_waitcnt lgkmcnt(0)
	v_cvt_pk_bf16_f32 v3, v4, v5
	ds_read2_b32 v[4:5], v28 offset0:132 offset1:165
	v_or_b32_e32 v6, s10, v1
	s_waitcnt lgkmcnt(0)
	v_cvt_pk_bf16_f32 v4, v4, v5
	v_mul_u32_u24_e32 v5, 0x1600, v6
	v_mov_b32_e32 v7, v11
	ds_read2_b32 v[8:9], v28 offset0:198 offset1:231
	v_lshlrev_b32_e32 v6, 1, v5
	v_lshl_add_u64 v[44:45], s[12:13], 0, v[20:21]
	s_waitcnt lgkmcnt(0)
	v_cvt_pk_bf16_f32 v5, v8, v9
	ds_read2_b32 v[8:9], v28 offset0:8 offset1:41
	v_lshl_add_u64 v[6:7], v[44:45], 0, v[6:7]
	global_store_dwordx4 v[6:7], v[2:5], off nt
	s_mov_b64 s[12:13], 0
	s_waitcnt lgkmcnt(0)
	v_cvt_pk_bf16_f32 v2, v8, v9
	v_or_b32_e32 v8, s10, v13
	v_mul_u32_u24_e32 v8, 0x1600, v8
	ds_read2_b32 v[4:5], v28 offset0:74 offset1:107
	v_mov_b32_e32 v9, v11
	v_lshlrev_b32_e32 v8, 1, v8
	s_waitcnt lgkmcnt(0)
	v_cvt_pk_bf16_f32 v3, v4, v5
	ds_read2_b32 v[4:5], v28 offset0:140 offset1:173
	v_lshl_add_u64 v[8:9], v[44:45], 0, v[8:9]
	s_waitcnt lgkmcnt(0)
	v_cvt_pk_bf16_f32 v4, v4, v5
	ds_read2_b32 v[6:7], v28 offset0:206 offset1:239
	s_waitcnt lgkmcnt(0)
	v_cvt_pk_bf16_f32 v5, v6, v7
	global_store_dwordx4 v[8:9], v[2:5], off nt
	v_or_b32_e32 v8, s10, v22
	ds_read2_b32 v[6:7], v28 offset0:16 offset1:49
	s_waitcnt lgkmcnt(0)
	v_cvt_pk_bf16_f32 v2, v6, v7
	ds_read2_b32 v[4:5], v28 offset0:82 offset1:115
	v_mul_u32_u24_e32 v8, 0x1600, v8
	s_waitcnt lgkmcnt(0)
	v_cvt_pk_bf16_f32 v3, v4, v5
	ds_read2_b32 v[4:5], v28 offset0:148 offset1:181
	v_mov_b32_e32 v9, v11
	v_lshlrev_b32_e32 v8, 1, v8
	s_waitcnt lgkmcnt(0)
	v_cvt_pk_bf16_f32 v4, v4, v5
	ds_read2_b32 v[6:7], v28 offset0:214 offset1:247
	s_waitcnt lgkmcnt(0)
	v_cvt_pk_bf16_f32 v5, v6, v7
	v_lshl_add_u64 v[8:9], v[44:45], 0, v[8:9]
	ds_read2_b32 v[6:7], v28 offset0:24 offset1:57
	global_store_dwordx4 v[8:9], v[2:5], off nt
	v_mov_b32_e32 v9, v11
	s_waitcnt lgkmcnt(0)
	v_cvt_pk_bf16_f32 v2, v6, v7
	ds_read2_b32 v[4:5], v28 offset0:90 offset1:123
	s_waitcnt lgkmcnt(0)
	v_cvt_pk_bf16_f32 v3, v4, v5
	ds_read2_b32 v[4:5], v28 offset0:156 offset1:189
	s_waitcnt lgkmcnt(0)
	v_cvt_pk_bf16_f32 v4, v4, v5
	v_or_b32_e32 v5, s10, v23
	v_mul_u32_u24_e32 v5, 0x1600, v5
	ds_read2_b32 v[6:7], v28 offset0:222 offset1:255
	v_lshlrev_b32_e32 v8, 1, v5
	s_waitcnt lgkmcnt(0)
	v_cvt_pk_bf16_f32 v5, v6, v7
	v_lshl_add_u64 v[6:7], v[44:45], 0, v[8:9]
	global_store_dwordx4 v[6:7], v[2:5], off nt
	s_waitcnt lgkmcnt(0)

.LBB0_22:
	ds_read2_b32 v[44:45], v28 offset1:33
	s_lshl_b32 s12, s17, 5
	v_readlane_b32 s13, v252, 28
	s_add_u32 s10, s13, s10
	v_readlane_b32 s13, v252, 29
	s_waitcnt vmcnt(1) lgkmcnt(0)
	v_mul_f32_e32 v21, v6, v44
	v_mul_f32_e32 v44, v7, v45
	v_cvt_pk_bf16_f32 v44, v21, v44
	ds_read2_b32 v[46:47], v28 offset0:66 offset1:99
	s_addc_u32 s13, s13, 0
	s_lshl_b32 s17, s17, 6
	s_and_b32 s17, s17, 0x3f00
	s_and_b32 s12, s12, 0x60
	s_waitcnt lgkmcnt(0)
	v_mul_f32_e32 v45, v9, v47
	v_mul_f32_e32 v21, v8, v46
	v_cvt_pk_bf16_f32 v45, v21, v45
	ds_read2_b32 v[46:47], v28 offset0:132 offset1:165
	s_or_b32 s12, s12, s17
	s_or_b32 s17, s12, 0x80
	s_lshl_b32 s12, s16, 1
	s_add_u32 s12, s10, s12
	s_waitcnt vmcnt(0) lgkmcnt(0)
	v_mul_f32_e32 v21, v2, v46
	v_mul_f32_e32 v46, v3, v47
	v_cvt_pk_bf16_f32 v46, v21, v46
	ds_read2_b32 v[48:49], v28 offset0:198 offset1:231
	s_addc_u32 s13, s13, 0
	v_mov_b32_e32 v21, v11
	v_lshl_add_u64 v[50:51], s[12:13], 0, v[20:21]
	v_mov_b32_e32 v53, v11
	s_waitcnt lgkmcnt(0)
	v_mul_f32_e32 v47, v5, v49
	v_mul_f32_e32 v21, v4, v48
	v_cvt_pk_bf16_f32 v47, v21, v47
	ds_read2_b32 v[48:49], v28 offset0:8 offset1:41
	v_or_b32_e32 v21, s17, v1
	v_lshlrev_b32_e32 v52, 12, v21
	v_lshl_add_u64 v[52:53], v[50:51], 0, v[52:53]
	global_store_dwordx4 v[52:53], v[44:47], off nt
	s_waitcnt lgkmcnt(0)
	v_mul_f32_e32 v21, v6, v48
	v_mov_b32_e32 v53, v11
	v_mul_f32_e32 v44, v7, v49
	v_cvt_pk_bf16_f32 v44, v21, v44
	ds_read2_b32 v[46:47], v28 offset0:74 offset1:107
	s_waitcnt lgkmcnt(0)
	v_mul_f32_e32 v45, v9, v47
	v_mul_f32_e32 v21, v8, v46
	v_cvt_pk_bf16_f32 v45, v21, v45
	ds_read2_b32 v[46:47], v28 offset0:140 offset1:173
	s_waitcnt lgkmcnt(0)
	v_mul_f32_e32 v21, v2, v46
	v_mul_f32_e32 v46, v3, v47
	v_cvt_pk_bf16_f32 v46, v21, v46
	ds_read2_b32 v[48:49], v28 offset0:206 offset1:239
	s_waitcnt lgkmcnt(0)
	v_mul_f32_e32 v47, v5, v49
	v_mul_f32_e32 v21, v4, v48
	v_cvt_pk_bf16_f32 v47, v21, v47
	ds_read2_b32 v[48:49], v28 offset0:16 offset1:49
	v_or_b32_e32 v21, s17, v13
	v_lshlrev_b32_e32 v52, 12, v21
	v_lshl_add_u64 v[52:53], v[50:51], 0, v[52:53]
	global_store_dwordx4 v[52:53], v[44:47], off nt
	s_waitcnt lgkmcnt(0)
	v_mul_f32_e32 v21, v6, v48
	v_mov_b32_e32 v53, v11
	v_mul_f32_e32 v44, v7, v49
	v_cvt_pk_bf16_f32 v44, v21, v44
	ds_read2_b32 v[46:47], v28 offset0:82 offset1:115
	s_waitcnt lgkmcnt(0)
	v_mul_f32_e32 v45, v9, v47
	v_mul_f32_e32 v21, v8, v46
	v_cvt_pk_bf16_f32 v45, v21, v45
	ds_read2_b32 v[46:47], v28 offset0:148 offset1:181
	s_waitcnt lgkmcnt(0)
	v_mul_f32_e32 v21, v2, v46
	v_mul_f32_e32 v46, v3, v47
	v_cvt_pk_bf16_f32 v46, v21, v46
	ds_read2_b32 v[48:49], v28 offset0:214 offset1:247
	s_waitcnt lgkmcnt(0)
	v_mul_f32_e32 v47, v5, v49
	v_mul_f32_e32 v21, v4, v48
	v_cvt_pk_bf16_f32 v47, v21, v47
	ds_read2_b32 v[48:49], v28 offset0:24 offset1:57
	v_or_b32_e32 v21, s17, v22
	v_lshlrev_b32_e32 v52, 12, v21
	v_lshl_add_u64 v[52:53], v[50:51], 0, v[52:53]
	global_store_dwordx4 v[52:53], v[44:47], off nt
	s_waitcnt lgkmcnt(0)
	v_mul_f32_e32 v6, v6, v48
	v_mul_f32_e32 v7, v7, v49
	v_cvt_pk_bf16_f32 v6, v6, v7
	ds_read2_b32 v[44:45], v28 offset0:90 offset1:123
	s_waitcnt lgkmcnt(0)
	v_mul_f32_e32 v7, v8, v44
	v_mul_f32_e32 v8, v9, v45
	v_cvt_pk_bf16_f32 v7, v7, v8
	ds_read2_b32 v[8:9], v28 offset0:156 offset1:189
	v_mov_b32_e32 v45, v11
	s_waitcnt lgkmcnt(0)
	v_mul_f32_e32 v2, v2, v8
	v_mul_f32_e32 v3, v3, v9
	v_cvt_pk_bf16_f32 v8, v2, v3
	ds_read2_b32 v[2:3], v28 offset0:222 offset1:255
	v_or_b32_e32 v9, s17, v23
	v_lshlrev_b32_e32 v44, 12, v9
	s_waitcnt lgkmcnt(0)
	v_mul_f32_e32 v2, v4, v2
	v_mul_f32_e32 v3, v5, v3
	v_cvt_pk_bf16_f32 v9, v2, v3
	v_lshl_add_u64 v[2:3], v[50:51], 0, v[44:45]
	global_store_dwordx4 v[2:3], v[6:9], off nt
	s_waitcnt lgkmcnt(0)

.LBB0_28:
	ds_read2_b32 v[44:45], v28 offset1:33
	s_lshl_b32 s12, s17, 5
	v_readlane_b32 s13, v252, 28
	s_add_u32 s10, s13, s10
	v_readlane_b32 s13, v252, 29
	s_waitcnt vmcnt(1) lgkmcnt(0)
	v_mul_f32_e32 v21, v6, v44
	v_mul_f32_e32 v44, v7, v45
	v_cvt_pk_bf16_f32 v44, v21, v44
	ds_read2_b32 v[46:47], v28 offset0:66 offset1:99
	s_addc_u32 s13, s13, 0
	s_lshl_b32 s17, s17, 6
	s_and_b32 s12, s12, 0x60
	s_and_b32 s17, s17, 0x3f00
	s_waitcnt lgkmcnt(0)
	v_mul_f32_e32 v45, v9, v47
	v_mul_f32_e32 v21, v8, v46
	v_cvt_pk_bf16_f32 v45, v21, v45
	ds_read2_b32 v[46:47], v28 offset0:132 offset1:165
	s_lshl_b32 s16, s16, 1
	s_or_b32 s17, s17, s12
	s_add_u32 s12, s10, s16
	s_addc_u32 s13, s13, 0
	s_waitcnt vmcnt(0) lgkmcnt(0)
	v_mul_f32_e32 v21, v2, v46
	v_mul_f32_e32 v46, v3, v47
	v_cvt_pk_bf16_f32 v46, v21, v46
	ds_read2_b32 v[48:49], v28 offset0:198 offset1:231
	v_mov_b32_e32 v21, v11
	v_lshl_add_u64 v[50:51], s[12:13], 0, v[20:21]
	v_mov_b32_e32 v53, v11
	s_waitcnt lgkmcnt(0)
	v_mul_f32_e32 v47, v5, v49
	v_mul_f32_e32 v21, v4, v48
	v_cvt_pk_bf16_f32 v47, v21, v47
	ds_read2_b32 v[48:49], v28 offset0:8 offset1:41
	v_or_b32_e32 v21, s17, v1
	v_lshlrev_b32_e32 v52, 12, v21
	v_lshl_add_u64 v[52:53], v[50:51], 0, v[52:53]
	global_store_dwordx4 v[52:53], v[44:47], off nt
	s_waitcnt lgkmcnt(0)
	v_mul_f32_e32 v21, v6, v48
	v_mov_b32_e32 v53, v11
	v_mul_f32_e32 v44, v7, v49
	v_cvt_pk_bf16_f32 v44, v21, v44
	ds_read2_b32 v[46:47], v28 offset0:74 offset1:107
	s_waitcnt lgkmcnt(0)
	v_mul_f32_e32 v45, v9, v47
	v_mul_f32_e32 v21, v8, v46
	v_cvt_pk_bf16_f32 v45, v21, v45
	ds_read2_b32 v[46:47], v28 offset0:140 offset1:173
	s_waitcnt lgkmcnt(0)
	v_mul_f32_e32 v21, v2, v46
	v_mul_f32_e32 v46, v3, v47
	v_cvt_pk_bf16_f32 v46, v21, v46
	ds_read2_b32 v[48:49], v28 offset0:206 offset1:239
	s_waitcnt lgkmcnt(0)
	v_mul_f32_e32 v47, v5, v49
	v_mul_f32_e32 v21, v4, v48
	v_cvt_pk_bf16_f32 v47, v21, v47
	ds_read2_b32 v[48:49], v28 offset0:16 offset1:49
	v_or_b32_e32 v21, s17, v13
	v_lshlrev_b32_e32 v52, 12, v21
	v_lshl_add_u64 v[52:53], v[50:51], 0, v[52:53]
	global_store_dwordx4 v[52:53], v[44:47], off nt
	s_waitcnt lgkmcnt(0)
	v_mul_f32_e32 v21, v6, v48
	v_mov_b32_e32 v53, v11
	v_mul_f32_e32 v44, v7, v49
	v_cvt_pk_bf16_f32 v44, v21, v44
	ds_read2_b32 v[46:47], v28 offset0:82 offset1:115
	s_waitcnt lgkmcnt(0)
	v_mul_f32_e32 v45, v9, v47
	v_mul_f32_e32 v21, v8, v46
	v_cvt_pk_bf16_f32 v45, v21, v45
	ds_read2_b32 v[46:47], v28 offset0:148 offset1:181
	s_waitcnt lgkmcnt(0)
	v_mul_f32_e32 v21, v2, v46
	v_mul_f32_e32 v46, v3, v47
	v_cvt_pk_bf16_f32 v46, v21, v46
	ds_read2_b32 v[48:49], v28 offset0:214 offset1:247
	s_waitcnt lgkmcnt(0)
	v_mul_f32_e32 v47, v5, v49
	v_mul_f32_e32 v21, v4, v48
	v_cvt_pk_bf16_f32 v47, v21, v47
	ds_read2_b32 v[48:49], v28 offset0:24 offset1:57
	v_or_b32_e32 v21, s17, v22
	v_lshlrev_b32_e32 v52, 12, v21
	v_lshl_add_u64 v[52:53], v[50:51], 0, v[52:53]
	global_store_dwordx4 v[52:53], v[44:47], off nt
	s_waitcnt lgkmcnt(0)
	v_mul_f32_e32 v6, v6, v48
	v_mul_f32_e32 v7, v7, v49
	v_cvt_pk_bf16_f32 v6, v6, v7
	ds_read2_b32 v[44:45], v28 offset0:90 offset1:123
	s_waitcnt lgkmcnt(0)
	v_mul_f32_e32 v7, v8, v44
	v_mul_f32_e32 v8, v9, v45
	v_cvt_pk_bf16_f32 v7, v7, v8
	ds_read2_b32 v[8:9], v28 offset0:156 offset1:189
	v_mov_b32_e32 v45, v11
	s_waitcnt lgkmcnt(0)
	v_mul_f32_e32 v2, v2, v8
	v_mul_f32_e32 v3, v3, v9
	v_cvt_pk_bf16_f32 v8, v2, v3
	ds_read2_b32 v[2:3], v28 offset0:222 offset1:255
	v_or_b32_e32 v9, s17, v23
	v_lshlrev_b32_e32 v44, 12, v9
	s_waitcnt lgkmcnt(0)
	v_mul_f32_e32 v2, v4, v2
	v_mul_f32_e32 v3, v5, v3
	v_cvt_pk_bf16_f32 v9, v2, v3
	v_lshl_add_u64 v[2:3], v[50:51], 0, v[44:45]
	global_store_dwordx4 v[2:3], v[6:9], off nt
	s_waitcnt lgkmcnt(0)

.LBB0_30:
	s_andn2_b64 vcc, exec, s[12:13]
	s_cbranch_vccnz .LBB0_32
	s_and_b32 s10, s21, 0x7800
	s_addk_i32 s10, 0xa000
	v_readlane_b32 s56, v252, 2
	s_lshl_b64 s[12:13], s[10:11], 13
	v_readlane_b32 s68, v252, 14
	v_readlane_b32 s69, v252, 15
	s_add_u32 s16, s68, s12
	s_addc_u32 s17, s69, s13
	s_lshl_b64 s[12:13], s[10:11], 12
	v_readlane_b32 s10, v252, 26
	s_add_u32 s18, s10, s12
	v_readlane_b32 s10, v252, 27
	s_addc_u32 s19, s10, s13
	s_and_b32 s22, s21, 0x7c0
	s_and_b32 s10, s3, 0x7e0
	v_or_b32_e32 v21, s22, v22
	s_lshl_b32 s12, s10, 2
	v_lshlrev_b32_e32 v44, 13, v21
	v_or_b32_e32 v21, s22, v23
	s_add_u32 s12, s16, s12
	v_lshlrev_b32_e32 v46, 13, v21
	v_or_b32_e32 v21, s22, v24
	s_addc_u32 s13, s17, 0
	v_or_b32_e32 v2, s22, v1
	v_or_b32_e32 v4, s22, v13
	v_lshlrev_b32_e32 v52, 13, v21
	v_or_b32_e32 v21, s22, v25
	v_lshl_add_u64 v[64:65], s[12:13], 0, v[10:11]
	v_lshlrev_b32_e32 v2, 13, v2
	v_mov_b32_e32 v3, v11
	v_lshlrev_b32_e32 v4, 13, v4
	v_mov_b32_e32 v5, v11
	v_mov_b32_e32 v45, v11
	v_mov_b32_e32 v47, v11
	v_mov_b32_e32 v53, v11
	v_lshlrev_b32_e32 v54, 13, v21
	v_mov_b32_e32 v55, v11
	v_lshl_add_u64 v[2:3], v[64:65], 0, v[2:3]
	v_lshl_add_u64 v[6:7], v[64:65], 0, v[4:5]
	v_lshl_add_u64 v[44:45], v[64:65], 0, v[44:45]
	v_lshl_add_u64 v[48:49], v[64:65], 0, v[46:47]
	v_lshl_add_u64 v[52:53], v[64:65], 0, v[52:53]
	v_lshl_add_u64 v[56:57], v[64:65], 0, v[54:55]
	global_load_dwordx4 v[2:5], v[2:3], off nt
	s_nop 0
	global_load_dwordx4 v[6:9], v[6:7], off nt
	s_nop 0
	global_load_dwordx4 v[44:47], v[44:45], off nt
	s_nop 0
	global_load_dwordx4 v[48:51], v[48:49], off nt
	s_nop 0
	global_load_dwordx4 v[52:55], v[52:53], off nt
	s_nop 0
	global_load_dwordx4 v[56:59], v[56:57], off nt
	v_or_b32_e32 v21, s22, v26
	v_lshlrev_b32_e32 v60, 13, v21
	v_mov_b32_e32 v61, v11
	v_lshl_add_u64 v[60:61], v[64:65], 0, v[60:61]
	v_or_b32_e32 v21, s22, v27
	global_load_dwordx4 v[60:63], v[60:61], off nt
	v_lshlrev_b32_e32 v66, 13, v21
	v_mov_b32_e32 v67, v11
	v_lshl_add_u64 v[64:65], v[64:65], 0, v[66:67]
	global_load_dwordx4 v[64:67], v[64:65], off nt
	s_lshl_b32 s12, s22, 1
	s_add_u32 s12, s18, s12
	v_mov_b32_e32 v21, v11
	s_addc_u32 s13, s19, 0
	v_readlane_b32 s57, v252, 3
	v_readlane_b32 s58, v252, 4
	v_readlane_b32 s59, v252, 5
	v_readlane_b32 s60, v252, 6
	v_readlane_b32 s61, v252, 7
	v_readlane_b32 s62, v252, 8
	v_readlane_b32 s63, v252, 9
	v_readlane_b32 s64, v252, 10
	v_readlane_b32 s65, v252, 11
	v_readlane_b32 s66, v252, 12
	v_readlane_b32 s67, v252, 13
	v_readlane_b32 s70, v252, 16
	v_readlane_b32 s71, v252, 17
	s_waitcnt vmcnt(7)
	ds_write2_b32 v29, v2, v3 offset1:1
	ds_write2_b32 v29, v4, v5 offset0:2 offset1:3
	s_waitcnt vmcnt(6)
	ds_write2_b32 v30, v6, v7 offset1:1
	ds_write2_b32 v31, v8, v9 offset1:1
	s_waitcnt vmcnt(5)
	ds_write2_b32 v32, v44, v45 offset1:1
	ds_write2_b32 v33, v46, v47 offset1:1
	s_waitcnt vmcnt(4)
	ds_write2_b32 v34, v48, v49 offset1:1
	ds_write2_b32 v35, v50, v51 offset1:1
	s_waitcnt vmcnt(3)
	ds_write2_b32 v36, v52, v53 offset1:1
	ds_write2_b32 v37, v54, v55 offset1:1
	s_waitcnt vmcnt(2)
	ds_write2_b32 v38, v56, v57 offset1:1
	ds_write2_b32 v39, v58, v59 offset1:1
	s_waitcnt vmcnt(1)
	ds_write2_b32 v40, v60, v61 offset1:1
	ds_write2_b32 v41, v62, v63 offset1:1
	s_waitcnt vmcnt(0)
	ds_write2_b32 v42, v64, v65 offset1:1
	ds_write2_b32 v43, v66, v67 offset1:1
	s_waitcnt lgkmcnt(0)
	ds_read2_b32 v[2:3], v28 offset1:33
	s_waitcnt lgkmcnt(0)
	v_cvt_pk_bf16_f32 v2, v2, v3
	ds_read2_b32 v[4:5], v28 offset0:66 offset1:99
	s_waitcnt lgkmcnt(0)
	v_cvt_pk_bf16_f32 v3, v4, v5
	ds_read2_b32 v[4:5], v28 offset0:132 offset1:165
	s_waitcnt lgkmcnt(0)
	v_cvt_pk_bf16_f32 v4, v4, v5
	v_or_b32_e32 v5, s10, v1
	v_mov_b32_e32 v7, v11
	ds_read2_b32 v[8:9], v28 offset0:198 offset1:231
	v_lshlrev_b32_e32 v6, 12, v5
	v_lshl_add_u64 v[44:45], s[12:13], 0, v[20:21]
	s_waitcnt lgkmcnt(0)
	v_cvt_pk_bf16_f32 v5, v8, v9
	ds_read2_b32 v[8:9], v28 offset0:8 offset1:41
	v_lshl_add_u64 v[6:7], v[44:45], 0, v[6:7]
	global_store_dwordx4 v[6:7], v[2:5], off nt
	s_waitcnt lgkmcnt(0)
	s_nop 0
	v_cvt_pk_bf16_f32 v2, v8, v9
	ds_read2_b32 v[4:5], v28 offset0:74 offset1:107
	v_or_b32_e32 v8, s10, v13
	s_waitcnt lgkmcnt(0)
	v_cvt_pk_bf16_f32 v3, v4, v5
	ds_read2_b32 v[4:5], v28 offset0:140 offset1:173
	v_mov_b32_e32 v9, v11
	v_lshlrev_b32_e32 v8, 12, v8
	s_waitcnt lgkmcnt(0)
	v_cvt_pk_bf16_f32 v4, v4, v5
	ds_read2_b32 v[6:7], v28 offset0:206 offset1:239
	s_waitcnt lgkmcnt(0)
	v_cvt_pk_bf16_f32 v5, v6, v7
	v_lshl_add_u64 v[8:9], v[44:45], 0, v[8:9]
	ds_read2_b32 v[6:7], v28 offset0:16 offset1:49
	global_store_dwordx4 v[8:9], v[2:5], off nt
	v_or_b32_e32 v8, s10, v22
	v_mov_b32_e32 v9, v11
	s_waitcnt lgkmcnt(0)
	v_cvt_pk_bf16_f32 v2, v6, v7
	ds_read2_b32 v[4:5], v28 offset0:82 offset1:115
	s_waitcnt lgkmcnt(0)
	v_cvt_pk_bf16_f32 v3, v4, v5
	ds_read2_b32 v[4:5], v28 offset0:148 offset1:181
	v_lshlrev_b32_e32 v8, 12, v8
	s_waitcnt lgkmcnt(0)
	v_cvt_pk_bf16_f32 v4, v4, v5
	ds_read2_b32 v[6:7], v28 offset0:214 offset1:247
	s_waitcnt lgkmcnt(0)
	v_cvt_pk_bf16_f32 v5, v6, v7
	v_lshl_add_u64 v[8:9], v[44:45], 0, v[8:9]
	ds_read2_b32 v[6:7], v28 offset0:24 offset1:57
	global_store_dwordx4 v[8:9], v[2:5], off nt
	v_mov_b32_e32 v9, v11
	s_waitcnt lgkmcnt(0)
	v_cvt_pk_bf16_f32 v2, v6, v7
	ds_read2_b32 v[4:5], v28 offset0:90 offset1:123
	s_waitcnt lgkmcnt(0)
	v_cvt_pk_bf16_f32 v3, v4, v5
	ds_read2_b32 v[4:5], v28 offset0:156 offset1:189
	s_waitcnt lgkmcnt(0)
	v_cvt_pk_bf16_f32 v4, v4, v5
	v_or_b32_e32 v5, s10, v23
	ds_read2_b32 v[6:7], v28 offset0:222 offset1:255
	v_lshlrev_b32_e32 v8, 12, v5
	s_waitcnt lgkmcnt(0)
	v_cvt_pk_bf16_f32 v5, v6, v7
	v_lshl_add_u64 v[6:7], v[44:45], 0, v[8:9]
	global_store_dwordx4 v[6:7], v[2:5], off nt
	s_waitcnt lgkmcnt(0)

.LBB0_37:
	ds_read2_b32 v[44:45], v28 offset1:33
	s_lshl_b64 s[12:13], s[10:11], 11
	s_lshl_b64 s[12:13], s[12:13], 1
	v_readlane_b32 s10, v252, 24
	s_add_u32 s10, s10, s12
	s_waitcnt vmcnt(1) lgkmcnt(0)
	v_mul_f32_e32 v21, v6, v44
	v_mul_f32_e32 v44, v7, v45
	v_cvt_pk_bf16_f32 v44, v21, v44
	ds_read2_b32 v[46:47], v28 offset0:66 offset1:99
	v_readlane_b32 s12, v252, 25
	s_addc_u32 s13, s12, s13
	s_lshl_b32 s12, s17, 1
	s_add_u32 s12, s10, s12
	s_waitcnt lgkmcnt(0)
	v_mul_f32_e32 v45, v9, v47
	v_mul_f32_e32 v21, v8, v46
	v_cvt_pk_bf16_f32 v45, v21, v45
	ds_read2_b32 v[46:47], v28 offset0:132 offset1:165
	v_mov_b32_e32 v21, v11
	s_addc_u32 s13, s13, 0
	v_lshl_add_u64 v[50:51], s[12:13], 0, v[20:21]
	v_mov_b32_e32 v53, v11
	s_waitcnt vmcnt(0) lgkmcnt(0)
	v_mul_f32_e32 v46, v2, v46
	v_mul_f32_e32 v47, v3, v47
	v_cvt_pk_bf16_f32 v46, v46, v47
	ds_read2_b32 v[48:49], v28 offset0:198 offset1:231
	s_waitcnt lgkmcnt(0)
	v_mul_f32_e32 v47, v5, v49
	v_mul_f32_e32 v21, v4, v48
	v_cvt_pk_bf16_f32 v47, v21, v47
	ds_read2_b32 v[48:49], v28 offset0:8 offset1:41
	v_or_b32_e32 v21, s16, v1
	v_lshlrev_b32_e32 v52, 12, v21
	v_lshl_add_u64 v[52:53], v[50:51], 0, v[52:53]
	global_store_dwordx4 v[52:53], v[44:47], off nt
	s_waitcnt lgkmcnt(0)
	v_mul_f32_e32 v21, v6, v48
	v_mov_b32_e32 v53, v11
	v_mul_f32_e32 v44, v7, v49
	v_cvt_pk_bf16_f32 v44, v21, v44
	ds_read2_b32 v[46:47], v28 offset0:74 offset1:107
	s_waitcnt lgkmcnt(0)
	v_mul_f32_e32 v45, v9, v47
	v_mul_f32_e32 v21, v8, v46
	v_cvt_pk_bf16_f32 v45, v21, v45
	ds_read2_b32 v[46:47], v28 offset0:140 offset1:173
	s_waitcnt lgkmcnt(0)
	v_mul_f32_e32 v21, v2, v46
	v_mul_f32_e32 v46, v3, v47
	v_cvt_pk_bf16_f32 v46, v21, v46
	ds_read2_b32 v[48:49], v28 offset0:206 offset1:239
	v_or_b32_e32 v21, s16, v13
	v_lshlrev_b32_e32 v52, 12, v21
	v_lshl_add_u64 v[52:53], v[50:51], 0, v[52:53]
	s_waitcnt lgkmcnt(0)
	v_mul_f32_e32 v47, v4, v48
	v_mul_f32_e32 v48, v5, v49
	v_cvt_pk_bf16_f32 v47, v47, v48
	ds_read2_b32 v[48:49], v28 offset0:16 offset1:49
	global_store_dwordx4 v[52:53], v[44:47], off nt
	v_mov_b32_e32 v53, v11
	s_waitcnt lgkmcnt(0)
	v_mul_f32_e32 v21, v6, v48
	v_mul_f32_e32 v44, v7, v49
	v_cvt_pk_bf16_f32 v44, v21, v44
	ds_read2_b32 v[46:47], v28 offset0:82 offset1:115
	s_waitcnt lgkmcnt(0)
	v_mul_f32_e32 v45, v9, v47
	v_mul_f32_e32 v21, v8, v46
	v_cvt_pk_bf16_f32 v45, v21, v45
	ds_read2_b32 v[46:47], v28 offset0:148 offset1:181
	s_waitcnt lgkmcnt(0)
	v_mul_f32_e32 v21, v2, v46
	v_mul_f32_e32 v46, v3, v47
	v_cvt_pk_bf16_f32 v46, v21, v46
	ds_read2_b32 v[48:49], v28 offset0:214 offset1:247
	v_or_b32_e32 v21, s16, v22
	v_lshlrev_b32_e32 v52, 12, v21
	v_lshl_add_u64 v[52:53], v[50:51], 0, v[52:53]
	s_waitcnt lgkmcnt(0)
	v_mul_f32_e32 v47, v4, v48
	v_mul_f32_e32 v48, v5, v49
	v_cvt_pk_bf16_f32 v47, v47, v48
	ds_read2_b32 v[48:49], v28 offset0:24 offset1:57
	global_store_dwordx4 v[52:53], v[44:47], off nt
	s_waitcnt lgkmcnt(0)
	v_mul_f32_e32 v6, v6, v48
	v_mul_f32_e32 v7, v7, v49
	v_cvt_pk_bf16_f32 v6, v6, v7
	ds_read2_b32 v[44:45], v28 offset0:90 offset1:123
	s_waitcnt lgkmcnt(0)
	v_mul_f32_e32 v7, v8, v44
	v_mul_f32_e32 v8, v9, v45
	v_cvt_pk_bf16_f32 v7, v7, v8
	ds_read2_b32 v[8:9], v28 offset0:156 offset1:189
	v_mov_b32_e32 v45, v11
	s_waitcnt lgkmcnt(0)
	v_mul_f32_e32 v2, v2, v8
	v_mul_f32_e32 v3, v3, v9
	v_cvt_pk_bf16_f32 v8, v2, v3
	ds_read2_b32 v[2:3], v28 offset0:222 offset1:255
	v_or_b32_e32 v9, s16, v23
	v_lshlrev_b32_e32 v44, 12, v9
	s_waitcnt lgkmcnt(0)
	v_mul_f32_e32 v2, v4, v2
	v_mul_f32_e32 v3, v5, v3
	v_cvt_pk_bf16_f32 v9, v2, v3
	v_lshl_add_u64 v[2:3], v[50:51], 0, v[44:45]
	global_store_dwordx4 v[2:3], v[6:9], off nt
	s_waitcnt lgkmcnt(0)

.LBB0_43:
	ds_read2_b32 v[44:45], v28 offset1:33
	s_lshl_b32 s10, s13, 1
	v_mov_b32_e32 v51, v11
	v_lshl_add_u64 v[52:53], v[18:19], 0, s[10:11]
	s_waitcnt vmcnt(1) lgkmcnt(0)
	v_mul_f32_e32 v21, v6, v44
	v_mul_f32_e32 v44, v7, v45
	v_cvt_pk_bf16_f32 v44, v21, v44
	ds_read2_b32 v[46:47], v28 offset0:66 offset1:99
	s_waitcnt lgkmcnt(0)
	v_mul_f32_e32 v45, v9, v47
	v_mul_f32_e32 v21, v8, v46
	v_cvt_pk_bf16_f32 v45, v21, v45
	ds_read2_b32 v[46:47], v28 offset0:132 offset1:165
	s_waitcnt vmcnt(0) lgkmcnt(0)
	v_mul_f32_e32 v21, v2, v46
	v_mul_f32_e32 v46, v3, v47
	v_cvt_pk_bf16_f32 v46, v21, v46
	ds_read2_b32 v[48:49], v28 offset0:198 offset1:231
	v_or_b32_e32 v21, s12, v1
	v_lshlrev_b32_e32 v50, 12, v21
	v_lshl_add_u64 v[50:51], v[52:53], 0, v[50:51]
	s_waitcnt lgkmcnt(0)
	v_mul_f32_e32 v47, v4, v48
	v_mul_f32_e32 v48, v5, v49
	v_cvt_pk_bf16_f32 v47, v47, v48
	ds_read2_b32 v[48:49], v28 offset0:8 offset1:41
	global_store_dwordx4 v[50:51], v[44:47], off nt
	v_mov_b32_e32 v51, v11
	s_waitcnt lgkmcnt(0)
	v_mul_f32_e32 v21, v6, v48
	v_mul_f32_e32 v44, v7, v49
	v_cvt_pk_bf16_f32 v44, v21, v44
	ds_read2_b32 v[46:47], v28 offset0:74 offset1:107
	s_waitcnt lgkmcnt(0)
	v_mul_f32_e32 v45, v9, v47
	v_mul_f32_e32 v21, v8, v46
	v_cvt_pk_bf16_f32 v45, v21, v45
	ds_read2_b32 v[46:47], v28 offset0:140 offset1:173
	s_waitcnt lgkmcnt(0)
	v_mul_f32_e32 v21, v2, v46
	v_mul_f32_e32 v46, v3, v47
	v_cvt_pk_bf16_f32 v46, v21, v46
	ds_read2_b32 v[48:49], v28 offset0:206 offset1:239
	v_or_b32_e32 v21, s12, v13
	v_lshlrev_b32_e32 v50, 12, v21
	v_lshl_add_u64 v[50:51], v[52:53], 0, v[50:51]
	s_waitcnt lgkmcnt(0)
	v_mul_f32_e32 v47, v4, v48
	v_mul_f32_e32 v48, v5, v49
	v_cvt_pk_bf16_f32 v47, v47, v48
	ds_read2_b32 v[48:49], v28 offset0:16 offset1:49
	global_store_dwordx4 v[50:51], v[44:47], off nt
	v_mov_b32_e32 v51, v11
	s_waitcnt lgkmcnt(0)
	v_mul_f32_e32 v21, v6, v48
	v_mul_f32_e32 v44, v7, v49
	v_cvt_pk_bf16_f32 v44, v21, v44
	ds_read2_b32 v[46:47], v28 offset0:82 offset1:115
	s_waitcnt lgkmcnt(0)
	v_mul_f32_e32 v45, v9, v47
	v_mul_f32_e32 v21, v8, v46
	v_cvt_pk_bf16_f32 v45, v21, v45
	ds_read2_b32 v[46:47], v28 offset0:148 offset1:181
	s_waitcnt lgkmcnt(0)
	v_mul_f32_e32 v21, v2, v46
	v_mul_f32_e32 v46, v3, v47
	v_cvt_pk_bf16_f32 v46, v21, v46
	ds_read2_b32 v[48:49], v28 offset0:214 offset1:247
	v_or_b32_e32 v21, s12, v22
	v_lshlrev_b32_e32 v50, 12, v21
	v_lshl_add_u64 v[50:51], v[52:53], 0, v[50:51]
	s_waitcnt lgkmcnt(0)
	v_mul_f32_e32 v47, v4, v48
	v_mul_f32_e32 v48, v5, v49
	v_cvt_pk_bf16_f32 v47, v47, v48
	ds_read2_b32 v[48:49], v28 offset0:24 offset1:57
	global_store_dwordx4 v[50:51], v[44:47], off nt
	s_waitcnt lgkmcnt(0)
	v_mul_f32_e32 v6, v6, v48
	v_mul_f32_e32 v7, v7, v49
	v_cvt_pk_bf16_f32 v6, v6, v7
	ds_read2_b32 v[44:45], v28 offset0:90 offset1:123
	s_waitcnt lgkmcnt(0)
	v_mul_f32_e32 v7, v8, v44
	v_mul_f32_e32 v8, v9, v45
	v_cvt_pk_bf16_f32 v7, v7, v8
	ds_read2_b32 v[8:9], v28 offset0:156 offset1:189
	v_mov_b32_e32 v45, v11
	s_waitcnt lgkmcnt(0)
	v_mul_f32_e32 v2, v2, v8
	v_mul_f32_e32 v3, v3, v9
	v_cvt_pk_bf16_f32 v8, v2, v3
	ds_read2_b32 v[2:3], v28 offset0:222 offset1:255
	v_or_b32_e32 v9, s12, v23
	v_lshlrev_b32_e32 v44, 12, v9
	s_waitcnt lgkmcnt(0)
	v_mul_f32_e32 v2, v4, v2
	v_mul_f32_e32 v3, v5, v3
	v_cvt_pk_bf16_f32 v9, v2, v3
	v_lshl_add_u64 v[2:3], v[52:53], 0, v[44:45]
	global_store_dwordx4 v[2:3], v[6:9], off nt
	s_waitcnt lgkmcnt(0)

.LBB0_45:
	s_andn2_b64 vcc, exec, s[12:13]
	s_cbranch_vccnz .LBB0_47
	s_and_b32 s10, s21, 0x3800
	s_addk_i32 s10, 0xd000
	s_lshl_b64 s[12:13], s[10:11], 13
	s_add_u32 s16, s50, s12
	s_addc_u32 s17, s51, s13
	s_lshl_b64 s[12:13], s[10:11], 12
	v_readlane_b32 s10, v252, 20
	s_add_u32 s18, s10, s12
	v_readlane_b32 s10, v252, 21
	s_addc_u32 s19, s10, s13
	s_and_b32 s22, s21, 0x7c0
	s_and_b32 s10, s3, 0x7e0
	v_or_b32_e32 v21, s22, v22
	s_lshl_b32 s12, s10, 2
	v_lshlrev_b32_e32 v44, 13, v21
	v_or_b32_e32 v21, s22, v23
	s_add_u32 s12, s16, s12
	v_lshlrev_b32_e32 v46, 13, v21
	v_or_b32_e32 v21, s22, v24
	s_addc_u32 s13, s17, 0
	v_or_b32_e32 v2, s22, v1
	v_or_b32_e32 v4, s22, v13
	v_lshlrev_b32_e32 v52, 13, v21
	v_or_b32_e32 v21, s22, v25
	v_lshl_add_u64 v[64:65], s[12:13], 0, v[10:11]
	v_lshlrev_b32_e32 v2, 13, v2
	v_mov_b32_e32 v3, v11
	v_lshlrev_b32_e32 v4, 13, v4
	v_mov_b32_e32 v5, v11
	v_mov_b32_e32 v45, v11
	v_mov_b32_e32 v47, v11
	v_mov_b32_e32 v53, v11
	v_lshlrev_b32_e32 v54, 13, v21
	v_mov_b32_e32 v55, v11
	v_lshl_add_u64 v[2:3], v[64:65], 0, v[2:3]
	v_lshl_add_u64 v[6:7], v[64:65], 0, v[4:5]
	v_lshl_add_u64 v[44:45], v[64:65], 0, v[44:45]
	v_lshl_add_u64 v[48:49], v[64:65], 0, v[46:47]
	v_lshl_add_u64 v[52:53], v[64:65], 0, v[52:53]
	v_lshl_add_u64 v[56:57], v[64:65], 0, v[54:55]
	global_load_dwordx4 v[2:5], v[2:3], off nt
	s_nop 0
	global_load_dwordx4 v[6:9], v[6:7], off nt
	s_nop 0
	global_load_dwordx4 v[44:47], v[44:45], off nt
	s_nop 0
	global_load_dwordx4 v[48:51], v[48:49], off nt
	s_nop 0
	global_load_dwordx4 v[52:55], v[52:53], off nt
	s_nop 0
	global_load_dwordx4 v[56:59], v[56:57], off nt
	v_or_b32_e32 v21, s22, v26
	v_lshlrev_b32_e32 v60, 13, v21
	v_mov_b32_e32 v61, v11
	v_lshl_add_u64 v[60:61], v[64:65], 0, v[60:61]
	v_or_b32_e32 v21, s22, v27
	global_load_dwordx4 v[60:63], v[60:61], off nt
	v_lshlrev_b32_e32 v66, 13, v21
	v_mov_b32_e32 v67, v11
	v_lshl_add_u64 v[64:65], v[64:65], 0, v[66:67]
	global_load_dwordx4 v[64:67], v[64:65], off nt
	s_lshl_b32 s12, s22, 1
	s_add_u32 s12, s18, s12
	v_mov_b32_e32 v21, v11
	s_addc_u32 s13, s19, 0
	s_waitcnt vmcnt(7)
	ds_write2_b32 v29, v2, v3 offset1:1
	ds_write2_b32 v29, v4, v5 offset0:2 offset1:3
	s_waitcnt vmcnt(6)
	ds_write2_b32 v30, v6, v7 offset1:1
	ds_write2_b32 v31, v8, v9 offset1:1
	s_waitcnt vmcnt(5)
	ds_write2_b32 v32, v44, v45 offset1:1
	ds_write2_b32 v33, v46, v47 offset1:1
	s_waitcnt vmcnt(4)
	ds_write2_b32 v34, v48, v49 offset1:1
	ds_write2_b32 v35, v50, v51 offset1:1
	s_waitcnt vmcnt(3)
	ds_write2_b32 v36, v52, v53 offset1:1
	ds_write2_b32 v37, v54, v55 offset1:1
	s_waitcnt vmcnt(2)
	ds_write2_b32 v38, v56, v57 offset1:1
	ds_write2_b32 v39, v58, v59 offset1:1
	s_waitcnt vmcnt(1)
	ds_write2_b32 v40, v60, v61 offset1:1
	ds_write2_b32 v41, v62, v63 offset1:1
	s_waitcnt vmcnt(0)
	ds_write2_b32 v42, v64, v65 offset1:1
	ds_write2_b32 v43, v66, v67 offset1:1
	s_waitcnt lgkmcnt(0)
	ds_read2_b32 v[2:3], v28 offset1:33
	s_waitcnt lgkmcnt(0)
	v_cvt_pk_bf16_f32 v2, v2, v3
	ds_read2_b32 v[4:5], v28 offset0:66 offset1:99
	s_waitcnt lgkmcnt(0)
	v_cvt_pk_bf16_f32 v3, v4, v5
	ds_read2_b32 v[4:5], v28 offset0:132 offset1:165
	s_waitcnt lgkmcnt(0)
	v_cvt_pk_bf16_f32 v4, v4, v5
	v_or_b32_e32 v5, s10, v1
	v_mov_b32_e32 v7, v11
	ds_read2_b32 v[8:9], v28 offset0:198 offset1:231
	v_lshlrev_b32_e32 v6, 12, v5
	v_lshl_add_u64 v[44:45], s[12:13], 0, v[20:21]
	s_waitcnt lgkmcnt(0)
	v_cvt_pk_bf16_f32 v5, v8, v9
	ds_read2_b32 v[8:9], v28 offset0:8 offset1:41
	v_lshl_add_u64 v[6:7], v[44:45], 0, v[6:7]
	global_store_dwordx4 v[6:7], v[2:5], off nt
	s_waitcnt lgkmcnt(0)
	s_nop 0
	v_cvt_pk_bf16_f32 v2, v8, v9
	ds_read2_b32 v[4:5], v28 offset0:74 offset1:107
	v_or_b32_e32 v8, s10, v13
	s_waitcnt lgkmcnt(0)
	v_cvt_pk_bf16_f32 v3, v4, v5
	ds_read2_b32 v[4:5], v28 offset0:140 offset1:173
	v_mov_b32_e32 v9, v11
	v_lshlrev_b32_e32 v8, 12, v8
	s_waitcnt lgkmcnt(0)
	v_cvt_pk_bf16_f32 v4, v4, v5
	ds_read2_b32 v[6:7], v28 offset0:206 offset1:239
	s_waitcnt lgkmcnt(0)
	v_cvt_pk_bf16_f32 v5, v6, v7
	v_lshl_add_u64 v[8:9], v[44:45], 0, v[8:9]
	ds_read2_b32 v[6:7], v28 offset0:16 offset1:49
	global_store_dwordx4 v[8:9], v[2:5], off nt
	v_or_b32_e32 v8, s10, v22
	v_mov_b32_e32 v9, v11
	s_waitcnt lgkmcnt(0)
	v_cvt_pk_bf16_f32 v2, v6, v7
	ds_read2_b32 v[4:5], v28 offset0:82 offset1:115
	s_waitcnt lgkmcnt(0)
	v_cvt_pk_bf16_f32 v3, v4, v5
	ds_read2_b32 v[4:5], v28 offset0:148 offset1:181
	v_lshlrev_b32_e32 v8, 12, v8
	s_waitcnt lgkmcnt(0)
	v_cvt_pk_bf16_f32 v4, v4, v5
	ds_read2_b32 v[6:7], v28 offset0:214 offset1:247
	s_waitcnt lgkmcnt(0)
	v_cvt_pk_bf16_f32 v5, v6, v7
	v_lshl_add_u64 v[8:9], v[44:45], 0, v[8:9]
	ds_read2_b32 v[6:7], v28 offset0:24 offset1:57
	global_store_dwordx4 v[8:9], v[2:5], off nt
	v_mov_b32_e32 v9, v11
	s_waitcnt lgkmcnt(0)
	v_cvt_pk_bf16_f32 v2, v6, v7
	ds_read2_b32 v[4:5], v28 offset0:90 offset1:123
	s_waitcnt lgkmcnt(0)
	v_cvt_pk_bf16_f32 v3, v4, v5
	ds_read2_b32 v[4:5], v28 offset0:156 offset1:189
	s_waitcnt lgkmcnt(0)
	v_cvt_pk_bf16_f32 v4, v4, v5
	v_or_b32_e32 v5, s10, v23
	ds_read2_b32 v[6:7], v28 offset0:222 offset1:255
	v_lshlrev_b32_e32 v8, 12, v5
	s_waitcnt lgkmcnt(0)
	v_cvt_pk_bf16_f32 v5, v6, v7
	v_lshl_add_u64 v[6:7], v[44:45], 0, v[8:9]
	global_store_dwordx4 v[6:7], v[2:5], off nt
	s_waitcnt lgkmcnt(0)
